# LN epi_resid loops: all 4 chunks stats+x loads issued up front, store waits removed; robust stats flush; dtype comment
# speedup vs baseline: 1.0884x; 1.0075x over previous
.Lstats_flush_0:
	s_waitcnt lgkmcnt(0)
	s_barrier
	v_readfirstlane_b32 s100, v92
	v_readfirstlane_b32 s101, v93
	v_readfirstlane_b32 s96, v234
	s_lshr_b32 s96, s96, 6
	s_lshl_b32 s96, s96, 4
	s_add_u32 s96, s96, 960
	s_sub_u32 s100, s100, s96
	s_subb_u32 s101, s101, 0
	s_lshr_b32 s96, s100, 3
	s_and_b32 s96, s96, 127
	v_lshrrev_b32_e32 v91, 1, v234
	v_subrev_u32_e32 v91, s96, v91
	v_and_b32_e32 v91, 127, v91
	v_and_b32_e32 v94, 1, v234
	v_lshlrev_b32_e32 v91, 3, v91
	v_lshl_add_u32 v91, v94, 2, v91
	v_lshlrev_b32_e32 v94, 2, v234
	v_add_u32_e32 v94, 68608, v94
	ds_read_b32 v90, v94
	s_nop 4
	s_waitcnt lgkmcnt(0)
	global_atomic_add_f32 v91, v90, s[100:101]
	s_branch .LBB0_1815

.LBB0_2065:
	v_lshl_add_u64 v[30:31], v[12:13], 0, s[20:21]
	v_add_co_u32_e32 v28, vcc, 0x3c000, v30
	s_nop 1
	v_addc_co_u32_e32 v29, vcc, 0, v31, vcc
	global_load_dwordx2 v[42:43], v[28:29], off
	v_lshl_add_u64 v[28:29], v[10:11], 0, v[8:9]
	s_waitcnt lgkmcnt(0)
	global_load_dwordx4 v[38:41], v[28:29], off
	v_lshl_add_u64 v[200:201], v[24:25], 0, s[20:21]
	v_add_co_u32_e32 v200, vcc, 0x3c000, v200
	s_nop 1
	v_addc_co_u32_e32 v201, vcc, 0, v201, vcc
	global_load_dwordx2 v[202:203], v[200:201], off
	v_add_co_u32_e32 v200, vcc, s54, v28
	s_nop 1
	v_addc_co_u32_e32 v201, vcc, 0, v29, vcc
	global_load_dwordx4 v[208:211], v[200:201], off
	v_lshl_add_u64 v[200:201], v[20:21], 0, s[20:21]
	v_add_co_u32_e32 v200, vcc, 0x3c000, v200
	s_nop 1
	v_addc_co_u32_e32 v201, vcc, 0, v201, vcc
	global_load_dwordx2 v[204:205], v[200:201], off
	v_add_co_u32_e32 v200, vcc, s55, v28
	s_nop 1
	v_addc_co_u32_e32 v201, vcc, 0, v29, vcc
	global_load_dwordx4 v[212:215], v[200:201], off
	v_lshl_add_u64 v[200:201], v[16:17], 0, s[20:21]
	v_add_co_u32_e32 v200, vcc, 0x3c000, v200
	s_nop 1
	v_addc_co_u32_e32 v201, vcc, 0, v201, vcc
	global_load_dwordx2 v[206:207], v[200:201], off
	v_add_co_u32_e32 v200, vcc, s56, v28
	s_nop 1
	v_addc_co_u32_e32 v201, vcc, 0, v29, vcc
	global_load_dwordx4 v[216:219], v[200:201], off
	s_waitcnt vmcnt(7)
	v_pk_mul_f32 v[46:47], v[42:43], s[14:15] op_sel:[1,0] op_sel_hi:[0,0]
	v_fma_f32 v42, -v47, v47, v46
	v_max_f32_e32 v42, 0, v42
	v_add_f32_e32 v42, 0x3727c5ac, v42
	v_mul_f32_e32 v43, 0x4b800000, v42
	v_cmp_gt_f32_e32 vcc, s53, v42
	s_waitcnt vmcnt(6)
	v_pk_add_f32 v[38:39], v[38:39], v[46:47] op_sel:[0,1] neg_lo:[0,1] neg_hi:[0,1]
	v_pk_add_f32 v[40:41], v[40:41], v[46:47] op_sel:[0,1] neg_lo:[0,1] neg_hi:[0,1]
	v_cndmask_b32_e32 v42, v42, v43, vcc
	v_rsq_f32_e32 v48, v42
	ds_read_b128 v[42:45], v37
	v_mul_f32_e32 v46, 0x45800000, v48
	v_cndmask_b32_e32 v46, v48, v46, vcc
	v_pk_mul_f32 v[38:39], v[38:39], v[46:47] op_sel_hi:[1,0]
	v_pk_mul_f32 v[40:41], v[40:41], v[46:47] op_sel_hi:[1,0]
	v_pk_fma_f32 v[38:39], v[0:1], v[38:39], v[4:5]
	v_pk_fma_f32 v[40:41], v[2:3], v[40:41], v[6:7]
	s_waitcnt lgkmcnt(0)
	v_pk_fma_f32 v[42:43], v[38:39], s[16:17], v[42:43] op_sel_hi:[1,0,1]
	v_pk_fma_f32 v[44:45], v[40:41], s[16:17], v[44:45] op_sel_hi:[1,0,1]
	v_pk_mul_f32 v[38:39], v[42:43], v[42:43]
	v_add_f32_e32 v46, v43, v42
	v_pk_mul_f32 v[40:41], v[44:45], v[44:45]
	v_add_f32_e32 v38, v39, v38
	v_add_f32_e32 v46, v44, v46
	v_add_f32_e32 v38, v40, v38
	v_add_f32_e32 v39, v45, v46
	v_add_f32_e32 v38, v41, v38
	ds_bpermute_b32 v40, v32, v39
	ds_bpermute_b32 v41, v32, v38
	v_lshl_add_u64 v[46:47], v[26:27], 0, v[8:9]
	global_store_dwordx4 v[46:47], v[42:45], off offset:-8
	s_waitcnt lgkmcnt(1)
	v_add_f32_e32 v39, v39, v40
	s_waitcnt lgkmcnt(0)
	v_add_f32_e32 v38, v38, v41
	ds_bpermute_b32 v40, v33, v39
	ds_bpermute_b32 v41, v33, v38
	s_waitcnt lgkmcnt(1)
	v_add_f32_e32 v39, v39, v40
	s_waitcnt lgkmcnt(0)
	v_add_f32_e32 v38, v38, v41
	ds_bpermute_b32 v40, v34, v39
	ds_bpermute_b32 v41, v34, v38
	s_waitcnt lgkmcnt(1)
	v_add_f32_e32 v39, v39, v40
	s_waitcnt lgkmcnt(0)
	v_add_f32_e32 v40, v38, v41
	ds_bpermute_b32 v38, v35, v39
	ds_bpermute_b32 v41, v35, v40
	s_waitcnt lgkmcnt(1)
	v_add_f32_e32 v38, v39, v38
	s_waitcnt lgkmcnt(0)
	v_add_f32_e32 v39, v40, v41
	ds_bpermute_b32 v40, v36, v38
	ds_bpermute_b32 v41, v36, v39
	s_and_saveexec_b64 s[22:23], s[0:1]
	s_cbranch_execz .LBB0_2067
	v_add_co_u32_e32 v30, vcc, 0x4c000, v30
	s_waitcnt lgkmcnt(1)
	v_add_f32_e32 v38, v38, v40
	v_addc_co_u32_e32 v31, vcc, 0, v31, vcc
	s_waitcnt lgkmcnt(0)
	v_add_f32_e32 v39, v39, v41
	v_mov_b32_e32 v92, v30
	v_mov_b32_e32 v93, v31
	v_and_b32_e32 v90, 0x3ff, v30
	v_add_u32_e32 v90, 68608, v90
	ds_write2_b32 v90, v38, v39 offset1:1
.LBB0_2067:
	s_or_b64 exec, exec, s[22:23]
	v_lshl_add_u64 v[30:31], v[24:25], 0, s[20:21]
	v_add_co_u32_e32 v38, vcc, 0x3c000, v30
	s_nop 1
	v_addc_co_u32_e32 v39, vcc, 0, v31, vcc
	s_waitcnt vmcnt(5)
	v_mov_b64_e32 v[42:43], v[202:203]
	v_add_co_u32_e32 v38, vcc, s54, v28
	v_pk_mul_f32 v[46:47], v[42:43], s[14:15] op_sel:[1,0] op_sel_hi:[0,0]
	v_addc_co_u32_e32 v39, vcc, 0, v29, vcc
	s_waitcnt lgkmcnt(0)
	v_mov_b64_e32 v[38:39], v[208:209]
	v_mov_b64_e32 v[40:41], v[210:211]
	v_fma_f32 v42, -v47, v47, v46
	v_max_f32_e32 v42, 0, v42
	v_add_f32_e32 v42, 0x3727c5ac, v42
	v_mul_f32_e32 v43, 0x4b800000, v42
	v_cmp_gt_f32_e32 vcc, s53, v42
	v_pk_add_f32 v[38:39], v[38:39], v[46:47] op_sel:[0,1] neg_lo:[0,1] neg_hi:[0,1]
	v_cndmask_b32_e32 v42, v42, v43, vcc
	v_rsq_f32_e32 v48, v42
	ds_read_b128 v[42:45], v37 offset:4224
	v_pk_add_f32 v[40:41], v[40:41], v[46:47] op_sel:[0,1] neg_lo:[0,1] neg_hi:[0,1]
	v_mul_f32_e32 v46, 0x45800000, v48
	v_cndmask_b32_e32 v46, v48, v46, vcc
	v_pk_mul_f32 v[38:39], v[38:39], v[46:47] op_sel_hi:[1,0]
	v_pk_mul_f32 v[40:41], v[40:41], v[46:47] op_sel_hi:[1,0]
	v_pk_fma_f32 v[38:39], v[0:1], v[38:39], v[4:5]
	v_pk_fma_f32 v[40:41], v[2:3], v[40:41], v[6:7]
	s_waitcnt lgkmcnt(0)
	v_pk_fma_f32 v[42:43], v[38:39], s[16:17], v[42:43] op_sel_hi:[1,0,1]
	v_pk_fma_f32 v[44:45], v[40:41], s[16:17], v[44:45] op_sel_hi:[1,0,1]
	v_pk_mul_f32 v[38:39], v[42:43], v[42:43]
	v_add_f32_e32 v46, v43, v42
	v_pk_mul_f32 v[40:41], v[44:45], v[44:45]
	v_add_f32_e32 v38, v39, v38
	v_add_f32_e32 v46, v44, v46
	v_add_f32_e32 v38, v40, v38
	v_add_f32_e32 v39, v45, v46
	v_add_f32_e32 v38, v41, v38
	ds_bpermute_b32 v40, v32, v39
	ds_bpermute_b32 v41, v32, v38
	v_lshl_add_u64 v[46:47], v[22:23], 0, v[8:9]
	global_store_dwordx4 v[46:47], v[42:45], off
	s_waitcnt lgkmcnt(1)
	v_add_f32_e32 v39, v39, v40
	s_waitcnt lgkmcnt(0)
	v_add_f32_e32 v38, v38, v41
	ds_bpermute_b32 v40, v33, v39
	ds_bpermute_b32 v41, v33, v38
	s_waitcnt lgkmcnt(1)
	v_add_f32_e32 v39, v39, v40
	s_waitcnt lgkmcnt(0)
	v_add_f32_e32 v38, v38, v41
	ds_bpermute_b32 v40, v34, v39
	ds_bpermute_b32 v41, v34, v38
	s_waitcnt lgkmcnt(1)
	v_add_f32_e32 v39, v39, v40
	s_waitcnt lgkmcnt(0)
	v_add_f32_e32 v40, v38, v41
	ds_bpermute_b32 v38, v35, v39
	ds_bpermute_b32 v41, v35, v40
	s_waitcnt lgkmcnt(1)
	v_add_f32_e32 v38, v39, v38
	s_waitcnt lgkmcnt(0)
	v_add_f32_e32 v39, v40, v41
	ds_bpermute_b32 v40, v36, v38
	ds_bpermute_b32 v41, v36, v39
	s_and_saveexec_b64 s[22:23], s[0:1]
	s_cbranch_execz .LBB0_2069
	v_add_co_u32_e32 v30, vcc, 0x4c000, v30
	s_waitcnt lgkmcnt(1)
	v_add_f32_e32 v38, v38, v40
	v_addc_co_u32_e32 v31, vcc, 0, v31, vcc
	s_waitcnt lgkmcnt(0)
	v_add_f32_e32 v39, v39, v41
	v_mov_b32_e32 v92, v30
	v_mov_b32_e32 v93, v31
	v_and_b32_e32 v90, 0x3ff, v30
	v_add_u32_e32 v90, 68608, v90
	ds_write2_b32 v90, v38, v39 offset1:1
.LBB0_2069:
	s_or_b64 exec, exec, s[22:23]
	v_lshl_add_u64 v[30:31], v[20:21], 0, s[20:21]
	v_add_co_u32_e32 v38, vcc, 0x3c000, v30
	s_nop 1
	v_addc_co_u32_e32 v39, vcc, 0, v31, vcc
	s_waitcnt vmcnt(4)
	v_mov_b64_e32 v[42:43], v[204:205]
	v_add_co_u32_e32 v38, vcc, s55, v28
	v_pk_mul_f32 v[46:47], v[42:43], s[14:15] op_sel:[1,0] op_sel_hi:[0,0]
	v_addc_co_u32_e32 v39, vcc, 0, v29, vcc
	s_waitcnt lgkmcnt(0)
	v_mov_b64_e32 v[38:39], v[212:213]
	v_mov_b64_e32 v[40:41], v[214:215]
	v_fma_f32 v42, -v47, v47, v46
	v_max_f32_e32 v42, 0, v42
	v_add_f32_e32 v42, 0x3727c5ac, v42
	v_mul_f32_e32 v43, 0x4b800000, v42
	v_cmp_gt_f32_e32 vcc, s53, v42
	v_pk_add_f32 v[38:39], v[38:39], v[46:47] op_sel:[0,1] neg_lo:[0,1] neg_hi:[0,1]
	v_cndmask_b32_e32 v42, v42, v43, vcc
	v_rsq_f32_e32 v48, v42
	ds_read_b128 v[42:45], v37 offset:8448
	v_pk_add_f32 v[40:41], v[40:41], v[46:47] op_sel:[0,1] neg_lo:[0,1] neg_hi:[0,1]
	v_mul_f32_e32 v46, 0x45800000, v48
	v_cndmask_b32_e32 v46, v48, v46, vcc
	v_pk_mul_f32 v[38:39], v[38:39], v[46:47] op_sel_hi:[1,0]
	v_pk_mul_f32 v[40:41], v[40:41], v[46:47] op_sel_hi:[1,0]
	v_pk_fma_f32 v[38:39], v[0:1], v[38:39], v[4:5]
	v_pk_fma_f32 v[40:41], v[2:3], v[40:41], v[6:7]
	s_waitcnt lgkmcnt(0)
	v_pk_fma_f32 v[42:43], v[38:39], s[16:17], v[42:43] op_sel_hi:[1,0,1]
	v_pk_fma_f32 v[44:45], v[40:41], s[16:17], v[44:45] op_sel_hi:[1,0,1]
	v_pk_mul_f32 v[38:39], v[42:43], v[42:43]
	v_add_f32_e32 v46, v43, v42
	v_pk_mul_f32 v[40:41], v[44:45], v[44:45]
	v_add_f32_e32 v38, v39, v38
	v_add_f32_e32 v46, v44, v46
	v_add_f32_e32 v38, v40, v38
	v_add_f32_e32 v39, v45, v46
	v_add_f32_e32 v38, v41, v38
	ds_bpermute_b32 v40, v32, v39
	ds_bpermute_b32 v41, v32, v38
	v_lshl_add_u64 v[46:47], v[18:19], 0, v[8:9]
	global_store_dwordx4 v[46:47], v[42:45], off
	s_waitcnt lgkmcnt(1)
	v_add_f32_e32 v39, v39, v40
	s_waitcnt lgkmcnt(0)
	v_add_f32_e32 v38, v38, v41
	ds_bpermute_b32 v40, v33, v39
	ds_bpermute_b32 v41, v33, v38
	s_waitcnt lgkmcnt(1)
	v_add_f32_e32 v39, v39, v40
	s_waitcnt lgkmcnt(0)
	v_add_f32_e32 v38, v38, v41
	ds_bpermute_b32 v40, v34, v39
	ds_bpermute_b32 v41, v34, v38
	s_waitcnt lgkmcnt(1)
	v_add_f32_e32 v39, v39, v40
	s_waitcnt lgkmcnt(0)
	v_add_f32_e32 v40, v38, v41
	ds_bpermute_b32 v38, v35, v39
	ds_bpermute_b32 v41, v35, v40
	s_waitcnt lgkmcnt(1)
	v_add_f32_e32 v38, v39, v38
	s_waitcnt lgkmcnt(0)
	v_add_f32_e32 v39, v40, v41
	ds_bpermute_b32 v40, v36, v38
	ds_bpermute_b32 v41, v36, v39
	s_and_saveexec_b64 s[22:23], s[0:1]
	s_cbranch_execz .LBB0_2071
	v_add_co_u32_e32 v30, vcc, 0x4c000, v30
	s_waitcnt lgkmcnt(1)
	v_add_f32_e32 v38, v38, v40
	v_addc_co_u32_e32 v31, vcc, 0, v31, vcc
	s_waitcnt lgkmcnt(0)
	v_add_f32_e32 v39, v39, v41
	v_mov_b32_e32 v92, v30
	v_mov_b32_e32 v93, v31
	v_and_b32_e32 v90, 0x3ff, v30
	v_add_u32_e32 v90, 68608, v90
	ds_write2_b32 v90, v38, v39 offset1:1
.LBB0_2071:
	s_or_b64 exec, exec, s[22:23]
	v_lshl_add_u64 v[30:31], v[16:17], 0, s[20:21]
	v_add_co_u32_e32 v38, vcc, 0x3c000, v30
	s_nop 1
	v_addc_co_u32_e32 v39, vcc, 0, v31, vcc
	s_waitcnt vmcnt(3)
	v_mov_b64_e32 v[42:43], v[206:207]
	v_add_co_u32_e32 v28, vcc, s56, v28
	s_nop 1
	v_addc_co_u32_e32 v29, vcc, 0, v29, vcc
	s_waitcnt lgkmcnt(0)
	v_mov_b64_e32 v[38:39], v[216:217]
	v_mov_b64_e32 v[40:41], v[218:219]
	v_pk_mul_f32 v[28:29], v[42:43], s[14:15] op_sel:[1,0] op_sel_hi:[0,0]
	v_fma_f32 v42, -v29, v29, v28
	v_max_f32_e32 v42, 0, v42
	v_add_f32_e32 v42, 0x3727c5ac, v42
	v_mul_f32_e32 v43, 0x4b800000, v42
	v_cmp_gt_f32_e32 vcc, s53, v42
	v_pk_add_f32 v[38:39], v[38:39], v[28:29] op_sel:[0,1] neg_lo:[0,1] neg_hi:[0,1]
	v_pk_add_f32 v[28:29], v[40:41], v[28:29] op_sel:[0,1] neg_lo:[0,1] neg_hi:[0,1]
	v_cndmask_b32_e32 v42, v42, v43, vcc
	v_rsq_f32_e32 v46, v42
	ds_read_b128 v[42:45], v37 offset:12672
	v_mul_f32_e32 v40, 0x45800000, v46
	v_cndmask_b32_e32 v40, v46, v40, vcc
	v_pk_mul_f32 v[38:39], v[38:39], v[40:41] op_sel_hi:[1,0]
	v_pk_mul_f32 v[28:29], v[28:29], v[40:41] op_sel_hi:[1,0]
	v_pk_fma_f32 v[38:39], v[0:1], v[38:39], v[4:5]
	v_pk_fma_f32 v[28:29], v[2:3], v[28:29], v[6:7]
	s_waitcnt lgkmcnt(0)
	v_pk_fma_f32 v[40:41], v[38:39], s[16:17], v[42:43] op_sel_hi:[1,0,1]
	v_pk_fma_f32 v[42:43], v[28:29], s[16:17], v[44:45] op_sel_hi:[1,0,1]
	v_pk_mul_f32 v[28:29], v[40:41], v[40:41]
	v_add_f32_e32 v44, v41, v40
	v_pk_mul_f32 v[38:39], v[42:43], v[42:43]
	v_add_f32_e32 v28, v29, v28
	v_add_f32_e32 v44, v42, v44
	v_add_f32_e32 v28, v38, v28
	v_add_f32_e32 v29, v43, v44
	v_add_f32_e32 v28, v39, v28
	ds_bpermute_b32 v38, v32, v29
	ds_bpermute_b32 v39, v32, v28
	v_lshl_add_u64 v[44:45], v[14:15], 0, v[8:9]
	global_store_dwordx4 v[44:45], v[40:43], off
	s_waitcnt lgkmcnt(1)
	v_add_f32_e32 v29, v29, v38
	s_waitcnt lgkmcnt(0)
	v_add_f32_e32 v28, v28, v39
	ds_bpermute_b32 v38, v33, v29
	ds_bpermute_b32 v39, v33, v28
	s_waitcnt lgkmcnt(1)
	v_add_f32_e32 v29, v29, v38
	s_waitcnt lgkmcnt(0)
	v_add_f32_e32 v28, v28, v39
	ds_bpermute_b32 v38, v34, v29
	ds_bpermute_b32 v39, v34, v28
	s_waitcnt lgkmcnt(1)
	v_add_f32_e32 v29, v29, v38
	s_waitcnt lgkmcnt(0)
	v_add_f32_e32 v38, v28, v39
	ds_bpermute_b32 v28, v35, v29
	ds_bpermute_b32 v39, v35, v38
	s_waitcnt lgkmcnt(1)
	v_add_f32_e32 v28, v29, v28
	s_waitcnt lgkmcnt(0)
	v_add_f32_e32 v29, v38, v39
	ds_bpermute_b32 v38, v36, v28
	ds_bpermute_b32 v39, v36, v29
	s_and_saveexec_b64 s[22:23], s[0:1]
	s_cbranch_execz .LBB0_2064
	s_waitcnt lgkmcnt(1)
	v_add_f32_e32 v38, v28, v38
	v_add_co_u32_e32 v28, vcc, 0x4c000, v30
	s_waitcnt lgkmcnt(0)
	v_add_f32_e32 v39, v29, v39
	v_addc_co_u32_e32 v29, vcc, 0, v31, vcc
	v_mov_b32_e32 v92, v28
	v_mov_b32_e32 v93, v29
	v_and_b32_e32 v90, 0x3ff, v28
	v_add_u32_e32 v90, 68608, v90
	ds_write2_b32 v90, v38, v39 offset1:1
	s_branch .LBB0_2064

.LBB0_3809:
	v_lshl_add_u64 v[28:29], s[30:31], 0, v[22:23]
	v_add_co_u32_e32 v26, vcc, 0x4c000, v28
	s_nop 1
	v_addc_co_u32_e32 v27, vcc, 0, v29, vcc
	global_load_dwordx2 v[40:41], v[26:27], off
	v_lshl_add_u64 v[26:27], v[8:9], 0, s[22:23]
	s_waitcnt lgkmcnt(0)
	global_load_dwordx4 v[36:39], v[26:27], off
	v_lshl_add_u64 v[200:201], s[30:31], 0, v[20:21]
	v_add_co_u32_e32 v200, vcc, 0x4c000, v200
	s_nop 1
	v_addc_co_u32_e32 v201, vcc, 0, v201, vcc
	global_load_dwordx2 v[202:203], v[200:201], off
	v_add_co_u32_e32 v200, vcc, s55, v26
	s_nop 1
	v_addc_co_u32_e32 v201, vcc, 0, v27, vcc
	global_load_dwordx4 v[208:211], v[200:201], off
	v_lshl_add_u64 v[200:201], s[30:31], 0, v[16:17]
	v_add_co_u32_e32 v200, vcc, 0x4c000, v200
	s_nop 1
	v_addc_co_u32_e32 v201, vcc, 0, v201, vcc
	global_load_dwordx2 v[204:205], v[200:201], off
	v_add_co_u32_e32 v200, vcc, s38, v26
	s_nop 1
	v_addc_co_u32_e32 v201, vcc, 0, v27, vcc
	global_load_dwordx4 v[212:215], v[200:201], off
	v_lshl_add_u64 v[200:201], s[30:31], 0, v[12:13]
	v_add_co_u32_e32 v200, vcc, 0x4c000, v200
	s_nop 1
	v_addc_co_u32_e32 v201, vcc, 0, v201, vcc
	global_load_dwordx2 v[206:207], v[200:201], off
	v_add_co_u32_e32 v200, vcc, s56, v26
	s_nop 1
	v_addc_co_u32_e32 v201, vcc, 0, v27, vcc
	global_load_dwordx4 v[216:219], v[200:201], off
	s_waitcnt vmcnt(7)
	v_pk_mul_f32 v[44:45], v[40:41], s[16:17] op_sel:[1,0] op_sel_hi:[0,0]
	v_fma_f32 v40, -v45, v45, v44
	v_max_f32_e32 v40, 0, v40
	v_add_f32_e32 v40, 0x3727c5ac, v40
	v_mul_f32_e32 v41, 0x4b800000, v40
	v_cmp_gt_f32_e32 vcc, s53, v40
	s_waitcnt vmcnt(6)
	v_pk_add_f32 v[36:37], v[36:37], v[44:45] op_sel:[0,1] neg_lo:[0,1] neg_hi:[0,1]
	v_pk_add_f32 v[38:39], v[38:39], v[44:45] op_sel:[0,1] neg_lo:[0,1] neg_hi:[0,1]
	v_cndmask_b32_e32 v40, v40, v41, vcc
	v_rsq_f32_e32 v46, v40
	ds_read_b128 v[40:43], v35
	v_mul_f32_e32 v44, 0x45800000, v46
	v_cndmask_b32_e32 v44, v46, v44, vcc
	v_pk_mul_f32 v[36:37], v[36:37], v[44:45] op_sel_hi:[1,0]
	v_pk_mul_f32 v[38:39], v[38:39], v[44:45] op_sel_hi:[1,0]
	v_pk_fma_f32 v[36:37], v[0:1], v[36:37], v[4:5]
	v_pk_fma_f32 v[38:39], v[2:3], v[38:39], v[6:7]
	s_waitcnt lgkmcnt(0)
	v_pk_fma_f32 v[40:41], v[36:37], s[18:19], v[40:41] op_sel_hi:[1,0,1]
	v_pk_fma_f32 v[42:43], v[38:39], s[18:19], v[42:43] op_sel_hi:[1,0,1]
	v_pk_mul_f32 v[36:37], v[40:41], v[40:41]
	v_add_f32_e32 v44, v41, v40
	v_pk_mul_f32 v[38:39], v[42:43], v[42:43]
	v_add_f32_e32 v36, v37, v36
	v_add_f32_e32 v44, v42, v44
	v_add_f32_e32 v36, v38, v36
	v_add_f32_e32 v37, v43, v44
	v_add_f32_e32 v36, v39, v36
	ds_bpermute_b32 v38, v30, v37
	ds_bpermute_b32 v39, v30, v36
	v_lshl_add_u64 v[44:45], s[30:31], 0, v[24:25]
	v_add_co_u32_e32 v44, vcc, s54, v44
	s_waitcnt lgkmcnt(1)
	v_add_f32_e32 v37, v37, v38
	s_waitcnt lgkmcnt(0)
	v_add_f32_e32 v36, v36, v39
	ds_bpermute_b32 v38, v31, v37
	ds_bpermute_b32 v39, v31, v36
	v_addc_co_u32_e32 v45, vcc, 0, v45, vcc
	global_store_dwordx4 v[44:45], v[40:43], off offset:3584
	s_waitcnt lgkmcnt(1)
	v_add_f32_e32 v37, v37, v38
	s_waitcnt lgkmcnt(0)
	v_add_f32_e32 v36, v36, v39
	ds_bpermute_b32 v38, v32, v37
	ds_bpermute_b32 v39, v32, v36
	s_waitcnt lgkmcnt(1)
	v_add_f32_e32 v37, v37, v38
	s_waitcnt lgkmcnt(0)
	v_add_f32_e32 v38, v36, v39
	ds_bpermute_b32 v36, v33, v37
	ds_bpermute_b32 v39, v33, v38
	s_waitcnt lgkmcnt(1)
	v_add_f32_e32 v36, v37, v36
	s_waitcnt lgkmcnt(0)
	v_add_f32_e32 v37, v38, v39
	ds_bpermute_b32 v38, v34, v36
	ds_bpermute_b32 v39, v34, v37
	s_and_saveexec_b64 s[24:25], s[0:1]
	s_cbranch_execz .LBB0_3811
	v_add_co_u32_e32 v28, vcc, 0x5c000, v28
	s_waitcnt lgkmcnt(1)
	v_add_f32_e32 v36, v36, v38
	v_addc_co_u32_e32 v29, vcc, 0, v29, vcc
	s_waitcnt lgkmcnt(0)
	v_add_f32_e32 v37, v37, v39
	v_mov_b32_e32 v92, v28
	v_mov_b32_e32 v93, v29
	v_and_b32_e32 v90, 0x3ff, v28
	v_add_u32_e32 v90, 68608, v90
	ds_write2_b32 v90, v36, v37 offset1:1
.LBB0_3811:
	s_or_b64 exec, exec, s[24:25]
	v_lshl_add_u64 v[28:29], s[30:31], 0, v[20:21]
	v_add_co_u32_e32 v36, vcc, 0x4c000, v28
	s_nop 1
	v_addc_co_u32_e32 v37, vcc, 0, v29, vcc
	s_waitcnt vmcnt(5)
	v_mov_b64_e32 v[40:41], v[202:203]
	v_add_co_u32_e32 v36, vcc, s55, v26
	v_pk_mul_f32 v[44:45], v[40:41], s[16:17] op_sel:[1,0] op_sel_hi:[0,0]
	v_addc_co_u32_e32 v37, vcc, 0, v27, vcc
	s_waitcnt lgkmcnt(0)
	v_mov_b64_e32 v[36:37], v[208:209]
	v_mov_b64_e32 v[38:39], v[210:211]
	v_fma_f32 v40, -v45, v45, v44
	v_max_f32_e32 v40, 0, v40
	v_add_f32_e32 v40, 0x3727c5ac, v40
	v_mul_f32_e32 v41, 0x4b800000, v40
	v_cmp_gt_f32_e32 vcc, s53, v40
	v_pk_add_f32 v[36:37], v[36:37], v[44:45] op_sel:[0,1] neg_lo:[0,1] neg_hi:[0,1]
	v_cndmask_b32_e32 v40, v40, v41, vcc
	v_rsq_f32_e32 v46, v40
	ds_read_b128 v[40:43], v35 offset:4224
	v_pk_add_f32 v[38:39], v[38:39], v[44:45] op_sel:[0,1] neg_lo:[0,1] neg_hi:[0,1]
	v_mul_f32_e32 v44, 0x45800000, v46
	v_cndmask_b32_e32 v44, v46, v44, vcc
	v_pk_mul_f32 v[36:37], v[36:37], v[44:45] op_sel_hi:[1,0]
	v_pk_mul_f32 v[38:39], v[38:39], v[44:45] op_sel_hi:[1,0]
	v_pk_fma_f32 v[36:37], v[0:1], v[36:37], v[4:5]
	v_pk_fma_f32 v[38:39], v[2:3], v[38:39], v[6:7]
	s_waitcnt lgkmcnt(0)
	v_pk_fma_f32 v[40:41], v[36:37], s[18:19], v[40:41] op_sel_hi:[1,0,1]
	v_pk_fma_f32 v[42:43], v[38:39], s[18:19], v[42:43] op_sel_hi:[1,0,1]
	v_pk_mul_f32 v[36:37], v[40:41], v[40:41]
	v_add_f32_e32 v44, v41, v40
	v_pk_mul_f32 v[38:39], v[42:43], v[42:43]
	v_add_f32_e32 v36, v37, v36
	v_add_f32_e32 v44, v42, v44
	v_add_f32_e32 v36, v38, v36
	v_add_f32_e32 v37, v43, v44
	v_add_f32_e32 v36, v39, v36
	ds_bpermute_b32 v38, v30, v37
	ds_bpermute_b32 v39, v30, v36
	v_lshl_add_u64 v[44:45], s[30:31], 0, v[18:19]
	v_add_co_u32_e32 v44, vcc, s54, v44
	s_waitcnt lgkmcnt(1)
	v_add_f32_e32 v37, v37, v38
	s_waitcnt lgkmcnt(0)
	v_add_f32_e32 v36, v36, v39
	ds_bpermute_b32 v38, v31, v37
	ds_bpermute_b32 v39, v31, v36
	v_addc_co_u32_e32 v45, vcc, 0, v45, vcc
	global_store_dwordx4 v[44:45], v[40:43], off offset:3584
	s_waitcnt lgkmcnt(1)
	v_add_f32_e32 v37, v37, v38
	s_waitcnt lgkmcnt(0)
	v_add_f32_e32 v36, v36, v39
	ds_bpermute_b32 v38, v32, v37
	ds_bpermute_b32 v39, v32, v36
	s_waitcnt lgkmcnt(1)
	v_add_f32_e32 v37, v37, v38
	s_waitcnt lgkmcnt(0)
	v_add_f32_e32 v38, v36, v39
	ds_bpermute_b32 v36, v33, v37
	ds_bpermute_b32 v39, v33, v38
	s_waitcnt lgkmcnt(1)
	v_add_f32_e32 v36, v37, v36
	s_waitcnt lgkmcnt(0)
	v_add_f32_e32 v37, v38, v39
	ds_bpermute_b32 v38, v34, v36
	ds_bpermute_b32 v39, v34, v37
	s_and_saveexec_b64 s[24:25], s[0:1]
	s_cbranch_execz .LBB0_3813
	v_add_co_u32_e32 v28, vcc, 0x5c000, v28
	s_waitcnt lgkmcnt(1)
	v_add_f32_e32 v36, v36, v38
	v_addc_co_u32_e32 v29, vcc, 0, v29, vcc
	s_waitcnt lgkmcnt(0)
	v_add_f32_e32 v37, v37, v39
	v_mov_b32_e32 v92, v28
	v_mov_b32_e32 v93, v29
	v_and_b32_e32 v90, 0x3ff, v28
	v_add_u32_e32 v90, 68608, v90
	ds_write2_b32 v90, v36, v37 offset1:1
.LBB0_3813:
	s_or_b64 exec, exec, s[24:25]
	v_lshl_add_u64 v[28:29], s[30:31], 0, v[16:17]
	v_add_co_u32_e32 v36, vcc, 0x4c000, v28
	s_nop 1
	v_addc_co_u32_e32 v37, vcc, 0, v29, vcc
	s_waitcnt vmcnt(4)
	v_mov_b64_e32 v[40:41], v[204:205]
	v_add_co_u32_e32 v36, vcc, s38, v26
	v_pk_mul_f32 v[44:45], v[40:41], s[16:17] op_sel:[1,0] op_sel_hi:[0,0]
	v_addc_co_u32_e32 v37, vcc, 0, v27, vcc
	s_waitcnt lgkmcnt(0)
	v_mov_b64_e32 v[36:37], v[212:213]
	v_mov_b64_e32 v[38:39], v[214:215]
	v_fma_f32 v40, -v45, v45, v44
	v_max_f32_e32 v40, 0, v40
	v_add_f32_e32 v40, 0x3727c5ac, v40
	v_mul_f32_e32 v41, 0x4b800000, v40
	v_cmp_gt_f32_e32 vcc, s53, v40
	v_pk_add_f32 v[36:37], v[36:37], v[44:45] op_sel:[0,1] neg_lo:[0,1] neg_hi:[0,1]
	v_cndmask_b32_e32 v40, v40, v41, vcc
	v_rsq_f32_e32 v46, v40
	ds_read_b128 v[40:43], v35 offset:8448
	v_pk_add_f32 v[38:39], v[38:39], v[44:45] op_sel:[0,1] neg_lo:[0,1] neg_hi:[0,1]
	v_mul_f32_e32 v44, 0x45800000, v46
	v_cndmask_b32_e32 v44, v46, v44, vcc
	v_pk_mul_f32 v[36:37], v[36:37], v[44:45] op_sel_hi:[1,0]
	v_pk_mul_f32 v[38:39], v[38:39], v[44:45] op_sel_hi:[1,0]
	v_pk_fma_f32 v[36:37], v[0:1], v[36:37], v[4:5]
	v_pk_fma_f32 v[38:39], v[2:3], v[38:39], v[6:7]
	s_waitcnt lgkmcnt(0)
	v_pk_fma_f32 v[40:41], v[36:37], s[18:19], v[40:41] op_sel_hi:[1,0,1]
	v_pk_fma_f32 v[42:43], v[38:39], s[18:19], v[42:43] op_sel_hi:[1,0,1]
	v_pk_mul_f32 v[36:37], v[40:41], v[40:41]
	v_add_f32_e32 v44, v41, v40
	v_pk_mul_f32 v[38:39], v[42:43], v[42:43]
	v_add_f32_e32 v36, v37, v36
	v_add_f32_e32 v44, v42, v44
	v_add_f32_e32 v36, v38, v36
	v_add_f32_e32 v37, v43, v44
	v_add_f32_e32 v36, v39, v36
	ds_bpermute_b32 v38, v30, v37
	ds_bpermute_b32 v39, v30, v36
	v_lshl_add_u64 v[44:45], s[30:31], 0, v[14:15]
	v_add_co_u32_e32 v44, vcc, s54, v44
	s_waitcnt lgkmcnt(1)
	v_add_f32_e32 v37, v37, v38
	s_waitcnt lgkmcnt(0)
	v_add_f32_e32 v36, v36, v39
	ds_bpermute_b32 v38, v31, v37
	ds_bpermute_b32 v39, v31, v36
	v_addc_co_u32_e32 v45, vcc, 0, v45, vcc
	global_store_dwordx4 v[44:45], v[40:43], off offset:3584
	s_waitcnt lgkmcnt(1)
	v_add_f32_e32 v37, v37, v38
	s_waitcnt lgkmcnt(0)
	v_add_f32_e32 v36, v36, v39
	ds_bpermute_b32 v38, v32, v37
	ds_bpermute_b32 v39, v32, v36
	s_waitcnt lgkmcnt(1)
	v_add_f32_e32 v37, v37, v38
	s_waitcnt lgkmcnt(0)
	v_add_f32_e32 v38, v36, v39
	ds_bpermute_b32 v36, v33, v37
	ds_bpermute_b32 v39, v33, v38
	s_waitcnt lgkmcnt(1)
	v_add_f32_e32 v36, v37, v36
	s_waitcnt lgkmcnt(0)
	v_add_f32_e32 v37, v38, v39
	ds_bpermute_b32 v38, v34, v36
	ds_bpermute_b32 v39, v34, v37
	s_and_saveexec_b64 s[24:25], s[0:1]
	s_cbranch_execz .LBB0_3815
	v_add_co_u32_e32 v28, vcc, 0x5c000, v28
	s_waitcnt lgkmcnt(1)
	v_add_f32_e32 v36, v36, v38
	v_addc_co_u32_e32 v29, vcc, 0, v29, vcc
	s_waitcnt lgkmcnt(0)
	v_add_f32_e32 v37, v37, v39
	v_mov_b32_e32 v92, v28
	v_mov_b32_e32 v93, v29
	v_and_b32_e32 v90, 0x3ff, v28
	v_add_u32_e32 v90, 68608, v90
	ds_write2_b32 v90, v36, v37 offset1:1
.LBB0_3815:
	s_or_b64 exec, exec, s[24:25]
	v_lshl_add_u64 v[28:29], s[30:31], 0, v[12:13]
	v_add_co_u32_e32 v36, vcc, 0x4c000, v28
	s_nop 1
	v_addc_co_u32_e32 v37, vcc, 0, v29, vcc
	s_waitcnt vmcnt(3)
	v_mov_b64_e32 v[40:41], v[206:207]
	v_add_co_u32_e32 v26, vcc, s56, v26
	s_nop 1
	v_addc_co_u32_e32 v27, vcc, 0, v27, vcc
	s_waitcnt lgkmcnt(0)
	v_mov_b64_e32 v[36:37], v[216:217]
	v_mov_b64_e32 v[38:39], v[218:219]
	v_pk_mul_f32 v[26:27], v[40:41], s[16:17] op_sel:[1,0] op_sel_hi:[0,0]
	v_fma_f32 v40, -v27, v27, v26
	v_max_f32_e32 v40, 0, v40
	v_add_f32_e32 v40, 0x3727c5ac, v40
	v_mul_f32_e32 v41, 0x4b800000, v40
	v_cmp_gt_f32_e32 vcc, s53, v40
	v_pk_add_f32 v[36:37], v[36:37], v[26:27] op_sel:[0,1] neg_lo:[0,1] neg_hi:[0,1]
	v_pk_add_f32 v[26:27], v[38:39], v[26:27] op_sel:[0,1] neg_lo:[0,1] neg_hi:[0,1]
	v_cndmask_b32_e32 v40, v40, v41, vcc
	v_rsq_f32_e32 v44, v40
	ds_read_b128 v[40:43], v35 offset:12672
	v_mul_f32_e32 v38, 0x45800000, v44
	v_cndmask_b32_e32 v38, v44, v38, vcc
	v_pk_mul_f32 v[36:37], v[36:37], v[38:39] op_sel_hi:[1,0]
	v_pk_mul_f32 v[26:27], v[26:27], v[38:39] op_sel_hi:[1,0]
	v_pk_fma_f32 v[36:37], v[0:1], v[36:37], v[4:5]
	v_pk_fma_f32 v[26:27], v[2:3], v[26:27], v[6:7]
	s_waitcnt lgkmcnt(0)
	v_pk_fma_f32 v[38:39], v[36:37], s[18:19], v[40:41] op_sel_hi:[1,0,1]
	v_pk_fma_f32 v[40:41], v[26:27], s[18:19], v[42:43] op_sel_hi:[1,0,1]
	v_pk_mul_f32 v[26:27], v[38:39], v[38:39]
	v_add_f32_e32 v42, v39, v38
	v_pk_mul_f32 v[36:37], v[40:41], v[40:41]
	v_add_f32_e32 v26, v27, v26
	v_add_f32_e32 v42, v40, v42
	v_add_f32_e32 v26, v36, v26
	v_add_f32_e32 v27, v41, v42
	v_add_f32_e32 v26, v37, v26
	ds_bpermute_b32 v36, v30, v27
	ds_bpermute_b32 v37, v30, v26
	v_lshl_add_u64 v[42:43], s[30:31], 0, v[10:11]
	v_add_co_u32_e32 v42, vcc, s54, v42
	s_waitcnt lgkmcnt(1)
	v_add_f32_e32 v27, v27, v36
	s_waitcnt lgkmcnt(0)
	v_add_f32_e32 v26, v26, v37
	ds_bpermute_b32 v36, v31, v27
	ds_bpermute_b32 v37, v31, v26
	v_addc_co_u32_e32 v43, vcc, 0, v43, vcc
	global_store_dwordx4 v[42:43], v[38:41], off offset:3584
	s_waitcnt lgkmcnt(1)
	v_add_f32_e32 v27, v27, v36
	s_waitcnt lgkmcnt(0)
	v_add_f32_e32 v26, v26, v37
	ds_bpermute_b32 v36, v32, v27
	ds_bpermute_b32 v37, v32, v26
	s_waitcnt lgkmcnt(1)
	v_add_f32_e32 v27, v27, v36
	s_waitcnt lgkmcnt(0)
	v_add_f32_e32 v36, v26, v37
	ds_bpermute_b32 v26, v33, v27
	ds_bpermute_b32 v37, v33, v36
	s_waitcnt lgkmcnt(1)
	v_add_f32_e32 v26, v27, v26
	s_waitcnt lgkmcnt(0)
	v_add_f32_e32 v27, v36, v37
	ds_bpermute_b32 v36, v34, v26
	ds_bpermute_b32 v37, v34, v27
	s_and_saveexec_b64 s[24:25], s[0:1]
	s_cbranch_execz .LBB0_3808
	s_waitcnt lgkmcnt(1)
	v_add_f32_e32 v36, v26, v36
	v_add_co_u32_e32 v26, vcc, 0x5c000, v28
	s_waitcnt lgkmcnt(0)
	v_add_f32_e32 v37, v27, v37
	v_addc_co_u32_e32 v27, vcc, 0, v29, vcc
	v_mov_b32_e32 v92, v26
	v_mov_b32_e32 v93, v27
	v_and_b32_e32 v90, 0x3ff, v26
	v_add_u32_e32 v90, 68608, v90
	ds_write2_b32 v90, v36, v37 offset1:1
	s_branch .LBB0_3808

.LBB0_4054:
	v_lshl_add_u64 v[30:31], v[12:13], 0, s[24:25]
	v_add_co_u32_e32 v28, vcc, 0x5c000, v30
	s_nop 1
	v_addc_co_u32_e32 v29, vcc, 0, v31, vcc
	global_load_dwordx2 v[42:43], v[28:29], off
	v_lshl_add_u64 v[28:29], v[10:11], 0, v[8:9]
	s_waitcnt lgkmcnt(0)
	global_load_dwordx4 v[38:41], v[28:29], off
	v_lshl_add_u64 v[200:201], v[24:25], 0, s[24:25]
	v_add_co_u32_e32 v200, vcc, 0x5c000, v200
	s_nop 1
	v_addc_co_u32_e32 v201, vcc, 0, v201, vcc
	global_load_dwordx2 v[202:203], v[200:201], off
	v_add_co_u32_e32 v200, vcc, s59, v28
	s_nop 1
	v_addc_co_u32_e32 v201, vcc, 0, v29, vcc
	global_load_dwordx4 v[208:211], v[200:201], off
	v_lshl_add_u64 v[200:201], v[20:21], 0, s[24:25]
	v_add_co_u32_e32 v200, vcc, 0x5c000, v200
	s_nop 1
	v_addc_co_u32_e32 v201, vcc, 0, v201, vcc
	global_load_dwordx2 v[204:205], v[200:201], off
	v_add_co_u32_e32 v200, vcc, s60, v28
	s_nop 1
	v_addc_co_u32_e32 v201, vcc, 0, v29, vcc
	global_load_dwordx4 v[212:215], v[200:201], off
	v_lshl_add_u64 v[200:201], v[16:17], 0, s[24:25]
	v_add_co_u32_e32 v200, vcc, 0x5c000, v200
	s_nop 1
	v_addc_co_u32_e32 v201, vcc, 0, v201, vcc
	global_load_dwordx2 v[206:207], v[200:201], off
	v_add_co_u32_e32 v200, vcc, s61, v28
	s_nop 1
	v_addc_co_u32_e32 v201, vcc, 0, v29, vcc
	global_load_dwordx4 v[216:219], v[200:201], off
	s_waitcnt vmcnt(7)
	v_pk_mul_f32 v[46:47], v[42:43], s[18:19] op_sel:[1,0] op_sel_hi:[0,0]
	v_fma_f32 v42, -v47, v47, v46
	v_max_f32_e32 v42, 0, v42
	v_add_f32_e32 v42, 0x3727c5ac, v42
	v_mul_f32_e32 v43, 0x4b800000, v42
	v_cmp_gt_f32_e32 vcc, s58, v42
	s_waitcnt vmcnt(6)
	v_pk_add_f32 v[38:39], v[38:39], v[46:47] op_sel:[0,1] neg_lo:[0,1] neg_hi:[0,1]
	v_pk_add_f32 v[40:41], v[40:41], v[46:47] op_sel:[0,1] neg_lo:[0,1] neg_hi:[0,1]
	v_cndmask_b32_e32 v42, v42, v43, vcc
	v_rsq_f32_e32 v48, v42
	ds_read_b128 v[42:45], v37
	v_mul_f32_e32 v46, 0x45800000, v48
	v_cndmask_b32_e32 v46, v48, v46, vcc
	v_pk_mul_f32 v[38:39], v[38:39], v[46:47] op_sel_hi:[1,0]
	v_pk_mul_f32 v[40:41], v[40:41], v[46:47] op_sel_hi:[1,0]
	v_pk_fma_f32 v[38:39], v[0:1], v[38:39], v[4:5]
	v_pk_fma_f32 v[40:41], v[2:3], v[40:41], v[6:7]
	s_waitcnt lgkmcnt(0)
	v_pk_fma_f32 v[42:43], v[38:39], s[20:21], v[42:43] op_sel_hi:[1,0,1]
	v_pk_fma_f32 v[44:45], v[40:41], s[20:21], v[44:45] op_sel_hi:[1,0,1]
	v_pk_mul_f32 v[38:39], v[42:43], v[42:43]
	v_add_f32_e32 v46, v43, v42
	v_pk_mul_f32 v[40:41], v[44:45], v[44:45]
	v_add_f32_e32 v38, v39, v38
	v_add_f32_e32 v46, v44, v46
	v_add_f32_e32 v38, v40, v38
	v_add_f32_e32 v39, v45, v46
	v_add_f32_e32 v38, v41, v38
	ds_bpermute_b32 v40, v32, v39
	ds_bpermute_b32 v41, v32, v38
	v_lshl_add_u64 v[46:47], v[26:27], 0, v[8:9]
	global_store_dwordx4 v[46:47], v[42:45], off offset:-8
	s_waitcnt lgkmcnt(1)
	v_add_f32_e32 v39, v39, v40
	s_waitcnt lgkmcnt(0)
	v_add_f32_e32 v38, v38, v41
	ds_bpermute_b32 v40, v33, v39
	ds_bpermute_b32 v41, v33, v38
	s_waitcnt lgkmcnt(1)
	v_add_f32_e32 v39, v39, v40
	s_waitcnt lgkmcnt(0)
	v_add_f32_e32 v38, v38, v41
	ds_bpermute_b32 v40, v34, v39
	ds_bpermute_b32 v41, v34, v38
	s_waitcnt lgkmcnt(1)
	v_add_f32_e32 v39, v39, v40
	s_waitcnt lgkmcnt(0)
	v_add_f32_e32 v40, v38, v41
	ds_bpermute_b32 v38, v35, v39
	ds_bpermute_b32 v41, v35, v40
	s_waitcnt lgkmcnt(1)
	v_add_f32_e32 v38, v39, v38
	s_waitcnt lgkmcnt(0)
	v_add_f32_e32 v39, v40, v41
	ds_bpermute_b32 v40, v36, v38
	ds_bpermute_b32 v41, v36, v39
	s_and_saveexec_b64 s[26:27], s[0:1]
	s_cbranch_execz .LBB0_4056
	v_add_co_u32_e32 v30, vcc, 0x6c000, v30
	s_waitcnt lgkmcnt(1)
	v_add_f32_e32 v38, v38, v40
	v_addc_co_u32_e32 v31, vcc, 0, v31, vcc
	s_waitcnt lgkmcnt(0)
	v_add_f32_e32 v39, v39, v41
	v_mov_b32_e32 v92, v30
	v_mov_b32_e32 v93, v31
	v_and_b32_e32 v90, 0x3ff, v30
	v_add_u32_e32 v90, 68608, v90
	ds_write2_b32 v90, v38, v39 offset1:1
.LBB0_4056:
	s_or_b64 exec, exec, s[26:27]
	v_lshl_add_u64 v[30:31], v[24:25], 0, s[24:25]
	v_add_co_u32_e32 v38, vcc, 0x5c000, v30
	s_nop 1
	v_addc_co_u32_e32 v39, vcc, 0, v31, vcc
	s_waitcnt vmcnt(5)
	v_mov_b64_e32 v[42:43], v[202:203]
	v_add_co_u32_e32 v38, vcc, s59, v28
	v_pk_mul_f32 v[46:47], v[42:43], s[18:19] op_sel:[1,0] op_sel_hi:[0,0]
	v_addc_co_u32_e32 v39, vcc, 0, v29, vcc
	s_waitcnt lgkmcnt(0)
	v_mov_b64_e32 v[38:39], v[208:209]
	v_mov_b64_e32 v[40:41], v[210:211]
	v_fma_f32 v42, -v47, v47, v46
	v_max_f32_e32 v42, 0, v42
	v_add_f32_e32 v42, 0x3727c5ac, v42
	v_mul_f32_e32 v43, 0x4b800000, v42
	v_cmp_gt_f32_e32 vcc, s58, v42
	v_pk_add_f32 v[38:39], v[38:39], v[46:47] op_sel:[0,1] neg_lo:[0,1] neg_hi:[0,1]
	v_cndmask_b32_e32 v42, v42, v43, vcc
	v_rsq_f32_e32 v48, v42
	ds_read_b128 v[42:45], v37 offset:4224
	v_pk_add_f32 v[40:41], v[40:41], v[46:47] op_sel:[0,1] neg_lo:[0,1] neg_hi:[0,1]
	v_mul_f32_e32 v46, 0x45800000, v48
	v_cndmask_b32_e32 v46, v48, v46, vcc
	v_pk_mul_f32 v[38:39], v[38:39], v[46:47] op_sel_hi:[1,0]
	v_pk_mul_f32 v[40:41], v[40:41], v[46:47] op_sel_hi:[1,0]
	v_pk_fma_f32 v[38:39], v[0:1], v[38:39], v[4:5]
	v_pk_fma_f32 v[40:41], v[2:3], v[40:41], v[6:7]
	s_waitcnt lgkmcnt(0)
	v_pk_fma_f32 v[42:43], v[38:39], s[20:21], v[42:43] op_sel_hi:[1,0,1]
	v_pk_fma_f32 v[44:45], v[40:41], s[20:21], v[44:45] op_sel_hi:[1,0,1]
	v_pk_mul_f32 v[38:39], v[42:43], v[42:43]
	v_add_f32_e32 v46, v43, v42
	v_pk_mul_f32 v[40:41], v[44:45], v[44:45]
	v_add_f32_e32 v38, v39, v38
	v_add_f32_e32 v46, v44, v46
	v_add_f32_e32 v38, v40, v38
	v_add_f32_e32 v39, v45, v46
	v_add_f32_e32 v38, v41, v38
	ds_bpermute_b32 v40, v32, v39
	ds_bpermute_b32 v41, v32, v38
	v_lshl_add_u64 v[46:47], v[22:23], 0, v[8:9]
	global_store_dwordx4 v[46:47], v[42:45], off
	s_waitcnt lgkmcnt(1)
	v_add_f32_e32 v39, v39, v40
	s_waitcnt lgkmcnt(0)
	v_add_f32_e32 v38, v38, v41
	ds_bpermute_b32 v40, v33, v39
	ds_bpermute_b32 v41, v33, v38
	s_waitcnt lgkmcnt(1)
	v_add_f32_e32 v39, v39, v40
	s_waitcnt lgkmcnt(0)
	v_add_f32_e32 v38, v38, v41
	ds_bpermute_b32 v40, v34, v39
	ds_bpermute_b32 v41, v34, v38
	s_waitcnt lgkmcnt(1)
	v_add_f32_e32 v39, v39, v40
	s_waitcnt lgkmcnt(0)
	v_add_f32_e32 v40, v38, v41
	ds_bpermute_b32 v38, v35, v39
	ds_bpermute_b32 v41, v35, v40
	s_waitcnt lgkmcnt(1)
	v_add_f32_e32 v38, v39, v38
	s_waitcnt lgkmcnt(0)
	v_add_f32_e32 v39, v40, v41
	ds_bpermute_b32 v40, v36, v38
	ds_bpermute_b32 v41, v36, v39
	s_and_saveexec_b64 s[26:27], s[0:1]
	s_cbranch_execz .LBB0_4058
	v_add_co_u32_e32 v30, vcc, 0x6c000, v30
	s_waitcnt lgkmcnt(1)
	v_add_f32_e32 v38, v38, v40
	v_addc_co_u32_e32 v31, vcc, 0, v31, vcc
	s_waitcnt lgkmcnt(0)
	v_add_f32_e32 v39, v39, v41
	v_mov_b32_e32 v92, v30
	v_mov_b32_e32 v93, v31
	v_and_b32_e32 v90, 0x3ff, v30
	v_add_u32_e32 v90, 68608, v90
	ds_write2_b32 v90, v38, v39 offset1:1
.LBB0_4058:
	s_or_b64 exec, exec, s[26:27]
	v_lshl_add_u64 v[30:31], v[20:21], 0, s[24:25]
	v_add_co_u32_e32 v38, vcc, 0x5c000, v30
	s_nop 1
	v_addc_co_u32_e32 v39, vcc, 0, v31, vcc
	s_waitcnt vmcnt(4)
	v_mov_b64_e32 v[42:43], v[204:205]
	v_add_co_u32_e32 v38, vcc, s60, v28
	v_pk_mul_f32 v[46:47], v[42:43], s[18:19] op_sel:[1,0] op_sel_hi:[0,0]
	v_addc_co_u32_e32 v39, vcc, 0, v29, vcc
	s_waitcnt lgkmcnt(0)
	v_mov_b64_e32 v[38:39], v[212:213]
	v_mov_b64_e32 v[40:41], v[214:215]
	v_fma_f32 v42, -v47, v47, v46
	v_max_f32_e32 v42, 0, v42
	v_add_f32_e32 v42, 0x3727c5ac, v42
	v_mul_f32_e32 v43, 0x4b800000, v42
	v_cmp_gt_f32_e32 vcc, s58, v42
	v_pk_add_f32 v[38:39], v[38:39], v[46:47] op_sel:[0,1] neg_lo:[0,1] neg_hi:[0,1]
	v_cndmask_b32_e32 v42, v42, v43, vcc
	v_rsq_f32_e32 v48, v42
	ds_read_b128 v[42:45], v37 offset:8448
	v_pk_add_f32 v[40:41], v[40:41], v[46:47] op_sel:[0,1] neg_lo:[0,1] neg_hi:[0,1]
	v_mul_f32_e32 v46, 0x45800000, v48
	v_cndmask_b32_e32 v46, v48, v46, vcc
	v_pk_mul_f32 v[38:39], v[38:39], v[46:47] op_sel_hi:[1,0]
	v_pk_mul_f32 v[40:41], v[40:41], v[46:47] op_sel_hi:[1,0]
	v_pk_fma_f32 v[38:39], v[0:1], v[38:39], v[4:5]
	v_pk_fma_f32 v[40:41], v[2:3], v[40:41], v[6:7]
	s_waitcnt lgkmcnt(0)
	v_pk_fma_f32 v[42:43], v[38:39], s[20:21], v[42:43] op_sel_hi:[1,0,1]
	v_pk_fma_f32 v[44:45], v[40:41], s[20:21], v[44:45] op_sel_hi:[1,0,1]
	v_pk_mul_f32 v[38:39], v[42:43], v[42:43]
	v_add_f32_e32 v46, v43, v42
	v_pk_mul_f32 v[40:41], v[44:45], v[44:45]
	v_add_f32_e32 v38, v39, v38
	v_add_f32_e32 v46, v44, v46
	v_add_f32_e32 v38, v40, v38
	v_add_f32_e32 v39, v45, v46
	v_add_f32_e32 v38, v41, v38
	ds_bpermute_b32 v40, v32, v39
	ds_bpermute_b32 v41, v32, v38
	v_lshl_add_u64 v[46:47], v[18:19], 0, v[8:9]
	global_store_dwordx4 v[46:47], v[42:45], off
	s_waitcnt lgkmcnt(1)
	v_add_f32_e32 v39, v39, v40
	s_waitcnt lgkmcnt(0)
	v_add_f32_e32 v38, v38, v41
	ds_bpermute_b32 v40, v33, v39
	ds_bpermute_b32 v41, v33, v38
	s_waitcnt lgkmcnt(1)
	v_add_f32_e32 v39, v39, v40
	s_waitcnt lgkmcnt(0)
	v_add_f32_e32 v38, v38, v41
	ds_bpermute_b32 v40, v34, v39
	ds_bpermute_b32 v41, v34, v38
	s_waitcnt lgkmcnt(1)
	v_add_f32_e32 v39, v39, v40
	s_waitcnt lgkmcnt(0)
	v_add_f32_e32 v40, v38, v41
	ds_bpermute_b32 v38, v35, v39
	ds_bpermute_b32 v41, v35, v40
	s_waitcnt lgkmcnt(1)
	v_add_f32_e32 v38, v39, v38
	s_waitcnt lgkmcnt(0)
	v_add_f32_e32 v39, v40, v41
	ds_bpermute_b32 v40, v36, v38
	ds_bpermute_b32 v41, v36, v39
	s_and_saveexec_b64 s[26:27], s[0:1]
	s_cbranch_execz .LBB0_4060
	v_add_co_u32_e32 v30, vcc, 0x6c000, v30
	s_waitcnt lgkmcnt(1)
	v_add_f32_e32 v38, v38, v40
	v_addc_co_u32_e32 v31, vcc, 0, v31, vcc
	s_waitcnt lgkmcnt(0)
	v_add_f32_e32 v39, v39, v41
	v_mov_b32_e32 v92, v30
	v_mov_b32_e32 v93, v31
	v_and_b32_e32 v90, 0x3ff, v30
	v_add_u32_e32 v90, 68608, v90
	ds_write2_b32 v90, v38, v39 offset1:1
.LBB0_4060:
	s_or_b64 exec, exec, s[26:27]
	v_lshl_add_u64 v[30:31], v[16:17], 0, s[24:25]
	v_add_co_u32_e32 v38, vcc, 0x5c000, v30
	s_nop 1
	v_addc_co_u32_e32 v39, vcc, 0, v31, vcc
	s_waitcnt vmcnt(3)
	v_mov_b64_e32 v[42:43], v[206:207]
	v_add_co_u32_e32 v28, vcc, s61, v28
	s_nop 1
	v_addc_co_u32_e32 v29, vcc, 0, v29, vcc
	s_waitcnt lgkmcnt(0)
	v_mov_b64_e32 v[38:39], v[216:217]
	v_mov_b64_e32 v[40:41], v[218:219]
	v_pk_mul_f32 v[28:29], v[42:43], s[18:19] op_sel:[1,0] op_sel_hi:[0,0]
	v_fma_f32 v42, -v29, v29, v28
	v_max_f32_e32 v42, 0, v42
	v_add_f32_e32 v42, 0x3727c5ac, v42
	v_mul_f32_e32 v43, 0x4b800000, v42
	v_cmp_gt_f32_e32 vcc, s58, v42
	v_pk_add_f32 v[38:39], v[38:39], v[28:29] op_sel:[0,1] neg_lo:[0,1] neg_hi:[0,1]
	v_pk_add_f32 v[28:29], v[40:41], v[28:29] op_sel:[0,1] neg_lo:[0,1] neg_hi:[0,1]
	v_cndmask_b32_e32 v42, v42, v43, vcc
	v_rsq_f32_e32 v46, v42
	ds_read_b128 v[42:45], v37 offset:12672
	v_mul_f32_e32 v40, 0x45800000, v46
	v_cndmask_b32_e32 v40, v46, v40, vcc
	v_pk_mul_f32 v[38:39], v[38:39], v[40:41] op_sel_hi:[1,0]
	v_pk_mul_f32 v[28:29], v[28:29], v[40:41] op_sel_hi:[1,0]
	v_pk_fma_f32 v[38:39], v[0:1], v[38:39], v[4:5]
	v_pk_fma_f32 v[28:29], v[2:3], v[28:29], v[6:7]
	s_waitcnt lgkmcnt(0)
	v_pk_fma_f32 v[40:41], v[38:39], s[20:21], v[42:43] op_sel_hi:[1,0,1]
	v_pk_fma_f32 v[42:43], v[28:29], s[20:21], v[44:45] op_sel_hi:[1,0,1]
	v_pk_mul_f32 v[28:29], v[40:41], v[40:41]
	v_add_f32_e32 v44, v41, v40
	v_pk_mul_f32 v[38:39], v[42:43], v[42:43]
	v_add_f32_e32 v28, v29, v28
	v_add_f32_e32 v44, v42, v44
	v_add_f32_e32 v28, v38, v28
	v_add_f32_e32 v29, v43, v44
	v_add_f32_e32 v28, v39, v28
	ds_bpermute_b32 v38, v32, v29
	ds_bpermute_b32 v39, v32, v28
	v_lshl_add_u64 v[44:45], v[14:15], 0, v[8:9]
	global_store_dwordx4 v[44:45], v[40:43], off
	s_waitcnt lgkmcnt(1)
	v_add_f32_e32 v29, v29, v38
	s_waitcnt lgkmcnt(0)
	v_add_f32_e32 v28, v28, v39
	ds_bpermute_b32 v38, v33, v29
	ds_bpermute_b32 v39, v33, v28
	s_waitcnt lgkmcnt(1)
	v_add_f32_e32 v29, v29, v38
	s_waitcnt lgkmcnt(0)
	v_add_f32_e32 v28, v28, v39
	ds_bpermute_b32 v38, v34, v29
	ds_bpermute_b32 v39, v34, v28
	s_waitcnt lgkmcnt(1)
	v_add_f32_e32 v29, v29, v38
	s_waitcnt lgkmcnt(0)
	v_add_f32_e32 v38, v28, v39
	ds_bpermute_b32 v28, v35, v29
	ds_bpermute_b32 v39, v35, v38
	s_waitcnt lgkmcnt(1)
	v_add_f32_e32 v28, v29, v28
	s_waitcnt lgkmcnt(0)
	v_add_f32_e32 v29, v38, v39
	ds_bpermute_b32 v38, v36, v28
	ds_bpermute_b32 v39, v36, v29
	s_and_saveexec_b64 s[26:27], s[0:1]
	s_cbranch_execz .LBB0_4053
	s_waitcnt lgkmcnt(1)
	v_add_f32_e32 v38, v28, v38
	v_add_co_u32_e32 v28, vcc, 0x6c000, v30
	s_waitcnt lgkmcnt(0)
	v_add_f32_e32 v39, v29, v39
	v_addc_co_u32_e32 v29, vcc, 0, v31, vcc
	v_mov_b32_e32 v92, v28
	v_mov_b32_e32 v93, v29
	v_and_b32_e32 v90, 0x3ff, v28
	v_add_u32_e32 v90, 68608, v90
	ds_write2_b32 v90, v38, v39 offset1:1
	s_branch .LBB0_4053
